# v27 + nt (streaming) policy on the final rmsnorm phase's 16-byte output stores
# baseline (speedup 1.0000x reference)
; __device__ __forceinline__ float bflo(unsigned w) { return __uint_as_float(w << 16); }
; __device__ __forceinline__ float bfhi(unsigned w) { return __uint_as_float(w & 0xffff0000u); }
; __device__ __forceinline__ void phase_final_norm(const bf16_t* Hb, const unsigned long long* ssq, const float* g, float* out, int gw, int ngw, int lane, float scale) {
;     for (int m = gw; m < MTOK; m += ngw) { const float rstd = scale / sqrtf((float)ssq[m] * (1.0f / 16777216.0f) * (1.0f / DM) + EPS);
;         const u32x4* xr = (const u32x4*)(Hb + (size_t)m * DM) + lane; f32x4* o = (f32x4*)(out + (size_t)m * DM); const f32x4* gr = (const f32x4*)g;
; #pragma unroll
;         for (int j = 0; j < 8; ++j) { const u32x4 r = xr[64 * j]; const int c4 = 2 * (64 * j + lane);
;             const f32x4 g0 = gr[c4], g1 = gr[c4 + 1];
;             o[c4] = (f32x4){bflo(r.x) * rstd * g0.x, bfhi(r.x) * rstd * g0.y, bflo(r.y) * rstd * g0.z, bfhi(r.y) * rstd * g0.w};
;             o[c4 + 1] = (f32x4){bflo(r.z) * rstd * g1.x, bfhi(r.z) * rstd * g1.y, bflo(r.w) * rstd * g1.z, bfhi(r.w) * rstd * g1.w}; } }
.LBB0_1880:
	v_add_co_u32_e32 v38, vcc, s8, v18
	v_lshl_add_u64 v[20:21], s[58:59], 0, v[16:17]
	s_nop 0
	v_addc_co_u32_e32 v39, vcc, 0, v19, vcc
	v_add_co_u32_e32 v22, vcc, s9, v18
	s_add_u32 s0, s58, s11
	s_nop 0
	v_addc_co_u32_e32 v23, vcc, 0, v19, vcc
	v_add_co_u32_e32 v40, vcc, s14, v20
	s_addc_u32 s1, s59, s12
	s_nop 0
	v_addc_co_u32_e32 v41, vcc, 0, v21, vcc
	v_add_co_u32_e32 v20, vcc, s15, v20
	global_load_dwordx4 v[26:29], v[2:3], off offset:16
	global_load_dwordx4 v[30:33], v[2:3], off
	v_addc_co_u32_e32 v21, vcc, 0, v21, vcc
	global_load_dwordx2 v[42:43], v1, s[0:1]
	global_load_dwordx4 v[34:37], v[20:21], off offset:-4096
	s_add_i32 s52, s52, s74
	s_add_u32 s11, s11, s2
	s_addc_u32 s12, s12, s3
	v_lshl_add_u64 v[16:17], v[16:17], 0, s[4:5]
	s_cmpk_lt_i32 s52, 0x2000
	s_waitcnt vmcnt(1)
	v_ffbh_u32_e32 v0, v43
	v_min_u32_e32 v0, 32, v0
	v_lshlrev_b64 v[42:43], v0, v[42:43]
	v_min_u32_e32 v42, 1, v42
	v_or_b32_e32 v42, v43, v42
	v_cvt_f32_u32_e32 v42, v42
	v_sub_u32_e32 v0, 32, v0
	s_waitcnt vmcnt(0)
	v_lshlrev_b32_e32 v44, 16, v34
	v_and_b32_e32 v45, 0xffff0000, v34
	v_ldexp_f32 v0, v42, v0
	v_mul_f32_e32 v0, 0x33800000, v0
	v_fmamk_f32 v0, v0, 0x39800000, v24
	v_mul_f32_e32 v42, 0x4f800000, v0
	v_cmp_gt_f32_e32 vcc, s13, v0
	v_lshlrev_b32_e32 v34, 16, v35
	v_and_b32_e32 v35, 0xffff0000, v35
	v_cndmask_b32_e32 v0, v0, v42, vcc
	v_sqrt_f32_e32 v42, v0
	v_lshlrev_b32_e32 v46, 16, v36
	v_and_b32_e32 v47, 0xffff0000, v36
	v_lshlrev_b32_e32 v36, 16, v37
	v_add_u32_e32 v43, -1, v42
	v_add_u32_e32 v48, 1, v42
	v_fma_f32 v49, -v43, v42, v0
	v_fma_f32 v50, -v48, v42, v0
	v_cmp_ge_f32_e64 s[0:1], 0, v49
	v_and_b32_e32 v37, 0xffff0000, v37
	s_nop 0
	v_cndmask_b32_e64 v42, v42, v43, s[0:1]
	v_cmp_lt_f32_e64 s[0:1], 0, v50
	s_nop 1
	v_cndmask_b32_e64 v42, v42, v48, s[0:1]
	v_mul_f32_e32 v43, 0x37800000, v42
	v_cndmask_b32_e32 v42, v42, v43, vcc
	v_cmp_class_f32_e32 vcc, v0, v25
	s_nop 1
	v_cndmask_b32_e32 v0, v42, v0, vcc
	v_div_scale_f32 v42, s[0:1], v0, v0, 1.0
	v_rcp_f32_e32 v48, v42
	v_div_scale_f32 v43, vcc, 1.0, v0, 1.0
	v_fma_f32 v49, -v42, v48, 1.0
	v_fmac_f32_e32 v48, v49, v48
	v_mul_f32_e32 v49, v43, v48
	v_fma_f32 v50, -v42, v49, v43
	v_fmac_f32_e32 v49, v50, v48
	v_fma_f32 v42, -v42, v49, v43
	v_div_fmas_f32 v42, v42, v48, v49
	v_div_fixup_f32 v0, v42, v0, 1.0
	v_pk_mul_f32 v[42:43], v[0:1], v[44:45] op_sel_hi:[0,1]
	v_pk_mul_f32 v[34:35], v[0:1], v[34:35] op_sel_hi:[0,1]
	v_pk_mul_f32 v[44:45], v[0:1], v[46:47] op_sel_hi:[0,1]
	v_pk_mul_f32 v[36:37], v[0:1], v[36:37] op_sel_hi:[0,1]
	v_pk_mul_f32 v[30:31], v[30:31], v[42:43]
	v_pk_mul_f32 v[32:33], v[32:33], v[34:35]
	v_pk_mul_f32 v[26:27], v[26:27], v[44:45]
	v_pk_mul_f32 v[28:29], v[28:29], v[36:37]
	global_store_dwordx4 v[18:19], v[30:33], off nt
	global_store_dwordx4 v[18:19], v[26:29], off offset:16 nt
	global_load_dwordx4 v[26:29], v[40:41], off offset:1024
	s_nop 0
	global_load_dwordx4 v[30:33], v[2:3], off offset:2048
	global_load_dwordx4 v[34:37], v[2:3], off offset:2064
	s_waitcnt vmcnt(2)
	v_lshlrev_b32_e32 v42, 16, v26
	v_and_b32_e32 v43, 0xffff0000, v26
	v_lshlrev_b32_e32 v26, 16, v27
	v_and_b32_e32 v27, 0xffff0000, v27
	v_lshlrev_b32_e32 v44, 16, v28
	v_and_b32_e32 v45, 0xffff0000, v28
	v_lshlrev_b32_e32 v28, 16, v29
	v_and_b32_e32 v29, 0xffff0000, v29
	v_pk_mul_f32 v[42:43], v[0:1], v[42:43] op_sel_hi:[0,1]
	v_pk_mul_f32 v[46:47], v[0:1], v[26:27] op_sel_hi:[0,1]
	v_pk_mul_f32 v[44:45], v[0:1], v[44:45] op_sel_hi:[0,1]
	v_pk_mul_f32 v[48:49], v[0:1], v[28:29] op_sel_hi:[0,1]
	s_waitcnt vmcnt(1)
	v_pk_mul_f32 v[26:27], v[30:31], v[42:43]
	v_pk_mul_f32 v[28:29], v[32:33], v[46:47]
	s_waitcnt vmcnt(0)
	v_pk_mul_f32 v[30:31], v[34:35], v[44:45]
	v_pk_mul_f32 v[32:33], v[36:37], v[48:49]
	global_store_dwordx4 v[18:19], v[26:29], off offset:2048 nt
	global_store_dwordx4 v[18:19], v[30:33], off offset:2064 nt
	global_load_dwordx4 v[26:29], v[40:41], off offset:2048
	s_nop 0
	global_load_dwordx4 v[30:33], v[4:5], off
	global_load_dwordx4 v[34:37], v[4:5], off offset:16
	s_waitcnt vmcnt(2)
	v_lshlrev_b32_e32 v42, 16, v26
	v_and_b32_e32 v43, 0xffff0000, v26
	v_lshlrev_b32_e32 v26, 16, v27
	v_and_b32_e32 v27, 0xffff0000, v27
	v_lshlrev_b32_e32 v44, 16, v28
	v_and_b32_e32 v45, 0xffff0000, v28
	v_lshlrev_b32_e32 v28, 16, v29
	v_and_b32_e32 v29, 0xffff0000, v29
	v_pk_mul_f32 v[42:43], v[0:1], v[42:43] op_sel_hi:[0,1]
	v_pk_mul_f32 v[46:47], v[0:1], v[26:27] op_sel_hi:[0,1]
	v_pk_mul_f32 v[44:45], v[0:1], v[44:45] op_sel_hi:[0,1]
	v_pk_mul_f32 v[48:49], v[0:1], v[28:29] op_sel_hi:[0,1]
	s_waitcnt vmcnt(1)
	v_pk_mul_f32 v[26:27], v[30:31], v[42:43]
	v_pk_mul_f32 v[28:29], v[32:33], v[46:47]
	s_waitcnt vmcnt(0)
	v_pk_mul_f32 v[30:31], v[34:35], v[44:45]
	v_pk_mul_f32 v[32:33], v[36:37], v[48:49]
	global_store_dwordx4 v[22:23], v[26:29], off offset:-4096 nt
	global_store_dwordx4 v[38:39], v[30:33], off offset:16 nt
	global_load_dwordx4 v[26:29], v[40:41], off offset:3072
	s_nop 0
	global_load_dwordx4 v[30:33], v[6:7], off
	global_load_dwordx4 v[34:37], v[6:7], off offset:16
	s_waitcnt vmcnt(2)
; __device__ __forceinline__ float bflo(unsigned w) { return __uint_as_float(w << 16); }
; __device__ __forceinline__ float bfhi(unsigned w) { return __uint_as_float(w & 0xffff0000u); }
; __device__ __forceinline__ void phase_final_norm(const bf16_t* Hb, const unsigned long long* ssq, const float* g, float* out, int gw, int ngw, int lane, float scale) {
;     for (int m = gw; m < MTOK; m += ngw) { const float rstd = scale / sqrtf((float)ssq[m] * (1.0f / 16777216.0f) * (1.0f / DM) + EPS);
;         const u32x4* xr = (const u32x4*)(Hb + (size_t)m * DM) + lane; f32x4* o = (f32x4*)(out + (size_t)m * DM); const f32x4* gr = (const f32x4*)g;
; #pragma unroll
;         for (int j = 0; j < 8; ++j) { const u32x4 r = xr[64 * j]; const int c4 = 2 * (64 * j + lane);
;             const f32x4 g0 = gr[c4], g1 = gr[c4 + 1];
;             o[c4] = (f32x4){bflo(r.x) * rstd * g0.x, bfhi(r.x) * rstd * g0.y, bflo(r.y) * rstd * g0.z, bfhi(r.y) * rstd * g0.w};
;             o[c4 + 1] = (f32x4){bflo(r.z) * rstd * g1.x, bfhi(r.z) * rstd * g1.y, bflo(r.w) * rstd * g1.z, bfhi(r.w) * rstd * g1.w}; } }
	v_lshlrev_b32_e32 v40, 16, v26
	v_and_b32_e32 v41, 0xffff0000, v26
	v_lshlrev_b32_e32 v26, 16, v27
	v_and_b32_e32 v27, 0xffff0000, v27
	v_lshlrev_b32_e32 v42, 16, v28
	v_and_b32_e32 v43, 0xffff0000, v28
	v_lshlrev_b32_e32 v28, 16, v29
	v_and_b32_e32 v29, 0xffff0000, v29
	v_pk_mul_f32 v[40:41], v[0:1], v[40:41] op_sel_hi:[0,1]
	v_pk_mul_f32 v[44:45], v[0:1], v[26:27] op_sel_hi:[0,1]
	v_pk_mul_f32 v[42:43], v[0:1], v[42:43] op_sel_hi:[0,1]
	v_pk_mul_f32 v[46:47], v[0:1], v[28:29] op_sel_hi:[0,1]
	s_waitcnt vmcnt(1)
	v_pk_mul_f32 v[26:27], v[30:31], v[40:41]
	v_pk_mul_f32 v[28:29], v[32:33], v[44:45]
	s_waitcnt vmcnt(0)
	v_pk_mul_f32 v[30:31], v[34:35], v[42:43]
	v_pk_mul_f32 v[32:33], v[36:37], v[46:47]
	global_store_dwordx4 v[38:39], v[26:29], off offset:2048 nt
	global_store_dwordx4 v[38:39], v[30:33], off offset:2064 nt
	global_load_dwordx4 v[26:29], v[20:21], off
	s_nop 0
	global_load_dwordx4 v[30:33], v[8:9], off
	global_load_dwordx4 v[34:37], v[8:9], off offset:16
	s_waitcnt vmcnt(2)
	v_lshlrev_b32_e32 v38, 16, v26
	v_and_b32_e32 v39, 0xffff0000, v26
	v_lshlrev_b32_e32 v26, 16, v27
	v_and_b32_e32 v27, 0xffff0000, v27
	v_lshlrev_b32_e32 v40, 16, v28
	v_and_b32_e32 v41, 0xffff0000, v28
	v_lshlrev_b32_e32 v28, 16, v29
	v_and_b32_e32 v29, 0xffff0000, v29
	v_pk_mul_f32 v[38:39], v[0:1], v[38:39] op_sel_hi:[0,1]
	v_pk_mul_f32 v[42:43], v[0:1], v[26:27] op_sel_hi:[0,1]
	v_pk_mul_f32 v[40:41], v[0:1], v[40:41] op_sel_hi:[0,1]
	v_pk_mul_f32 v[44:45], v[0:1], v[28:29] op_sel_hi:[0,1]
	s_waitcnt vmcnt(1)
	v_pk_mul_f32 v[26:27], v[30:31], v[38:39]
	v_pk_mul_f32 v[28:29], v[32:33], v[42:43]
	s_waitcnt vmcnt(0)
	v_pk_mul_f32 v[30:31], v[34:35], v[40:41]
	v_pk_mul_f32 v[32:33], v[36:37], v[44:45]
	global_store_dwordx4 v[22:23], v[26:29], off nt
	global_store_dwordx4 v[22:23], v[30:33], off offset:16 nt
	global_load_dwordx4 v[26:29], v[20:21], off offset:1024
	s_nop 0
	global_load_dwordx4 v[30:33], v[10:11], off
	global_load_dwordx4 v[34:37], v[10:11], off offset:16
	s_waitcnt vmcnt(2)
	v_lshlrev_b32_e32 v38, 16, v26
	v_and_b32_e32 v39, 0xffff0000, v26
	v_lshlrev_b32_e32 v26, 16, v27
	v_and_b32_e32 v27, 0xffff0000, v27
	v_lshlrev_b32_e32 v40, 16, v28
	v_and_b32_e32 v41, 0xffff0000, v28
	v_lshlrev_b32_e32 v28, 16, v29
	v_and_b32_e32 v29, 0xffff0000, v29
	v_pk_mul_f32 v[38:39], v[0:1], v[38:39] op_sel_hi:[0,1]
	v_pk_mul_f32 v[42:43], v[0:1], v[26:27] op_sel_hi:[0,1]
	v_pk_mul_f32 v[40:41], v[0:1], v[40:41] op_sel_hi:[0,1]
	v_pk_mul_f32 v[44:45], v[0:1], v[28:29] op_sel_hi:[0,1]
	s_waitcnt vmcnt(1)
	v_pk_mul_f32 v[26:27], v[30:31], v[38:39]
	v_pk_mul_f32 v[28:29], v[32:33], v[42:43]
	s_waitcnt vmcnt(0)
	v_pk_mul_f32 v[30:31], v[34:35], v[40:41]
	v_pk_mul_f32 v[32:33], v[36:37], v[44:45]
	global_store_dwordx4 v[22:23], v[26:29], off offset:2048 nt
	global_store_dwordx4 v[22:23], v[30:33], off offset:2064 nt
	global_load_dwordx4 v[26:29], v[20:21], off offset:2048
	s_nop 0
	global_load_dwordx4 v[30:33], v[12:13], off
	global_load_dwordx4 v[34:37], v[12:13], off offset:16
	v_add_co_u32_e32 v38, vcc, s10, v18
	s_waitcnt vmcnt(2)
	v_lshlrev_b32_e32 v22, 16, v26
	v_and_b32_e32 v23, 0xffff0000, v26
	v_lshlrev_b32_e32 v26, 16, v27
	v_and_b32_e32 v27, 0xffff0000, v27
	v_lshlrev_b32_e32 v40, 16, v28
	v_and_b32_e32 v41, 0xffff0000, v28
	v_lshlrev_b32_e32 v28, 16, v29
	v_and_b32_e32 v29, 0xffff0000, v29
	v_pk_mul_f32 v[22:23], v[0:1], v[22:23] op_sel_hi:[0,1]
	v_pk_mul_f32 v[42:43], v[0:1], v[26:27] op_sel_hi:[0,1]
	v_addc_co_u32_e32 v39, vcc, 0, v19, vcc
	v_pk_mul_f32 v[40:41], v[0:1], v[40:41] op_sel_hi:[0,1]
	v_pk_mul_f32 v[44:45], v[0:1], v[28:29] op_sel_hi:[0,1]
	s_waitcnt vmcnt(1)
	v_pk_mul_f32 v[26:27], v[30:31], v[22:23]
	v_pk_mul_f32 v[28:29], v[32:33], v[42:43]
	s_waitcnt vmcnt(0)
	v_pk_mul_f32 v[30:31], v[34:35], v[40:41]
	v_pk_mul_f32 v[32:33], v[36:37], v[44:45]
	global_store_dwordx4 v[38:39], v[26:29], off nt
	global_store_dwordx4 v[38:39], v[30:33], off offset:16 nt
	global_load_dwordx4 v[26:29], v[20:21], off offset:3072
	s_nop 0
	global_load_dwordx4 v[30:33], v[14:15], off
	global_load_dwordx4 v[34:37], v[14:15], off offset:16
	v_lshl_add_u64 v[18:19], v[18:19], 0, s[6:7]
	s_waitcnt vmcnt(2)
	v_lshlrev_b32_e32 v20, 16, v26
	v_and_b32_e32 v21, 0xffff0000, v26
	v_lshlrev_b32_e32 v22, 16, v27
	v_and_b32_e32 v23, 0xffff0000, v27
	v_lshlrev_b32_e32 v26, 16, v28
	v_and_b32_e32 v27, 0xffff0000, v28
	v_lshlrev_b32_e32 v28, 16, v29
	v_and_b32_e32 v29, 0xffff0000, v29
	v_pk_mul_f32 v[20:21], v[0:1], v[20:21] op_sel_hi:[0,1]
	v_pk_mul_f32 v[22:23], v[0:1], v[22:23] op_sel_hi:[0,1]
	v_pk_mul_f32 v[26:27], v[0:1], v[26:27] op_sel_hi:[0,1]
	v_pk_mul_f32 v[28:29], v[0:1], v[28:29] op_sel_hi:[0,1]
	s_waitcnt vmcnt(1)
	v_pk_mul_f32 v[20:21], v[30:31], v[20:21]
	v_pk_mul_f32 v[22:23], v[32:33], v[22:23]
	s_waitcnt vmcnt(0)
	v_pk_mul_f32 v[26:27], v[34:35], v[26:27]
	v_pk_mul_f32 v[28:29], v[36:37], v[28:29]
	global_store_dwordx4 v[38:39], v[20:23], off offset:2048 nt
	global_store_dwordx4 v[38:39], v[26:29], off offset:2064 nt
	s_cbranch_scc1 .LBB0_1880
